# FFN-up: wave groups stay staggered across unit boundaries (re-align/re-stagger barriers only around the last unit), epilogue of one group overlaps the other group's MFMA block
# speedup vs baseline: 1.0022x; 1.0022x over previous
; #define PG8_BAR __builtin_amdgcn_s_barrier()
; template <class Epi, class Sched>
; __device__ __forceinline__ void gemm_phase(const int tid, LAS unsigned char* lds, const int lda, const int ldb, const int K, const Sched& S, const Epi& E) {
;     ...
;         if (wr == 0) PG8_BAR;
;         if (MK_EPI2 && Epi::IDEM) E(acc, cur, wr, wc, fr, fq, es0, es1);
;         E(acc, cur, wr, wc, fr, fq, es0, es1);
;         if (!has_next) break;
;         E.pre(nxt, wr, wc, fr, fq, es0, es1);
;         E.init(acc, nxt, wr, wc, fr, fq);
;         cur = nxt; cA = nA; cB = nB; ++ui;
;         if (wr == 1) PG8_BAR;
.Lkexit_896:
	s_mov_b32 s65, 0x12000
	s_mov_b32 s64, 0x14000
	s_mov_b32 s66, 0x16000
	s_mov_b32 s67, 0x18000
	s_cmp_lg_u64 s[36:37], 0
	s_cbranch_scc1 .LBB0_899
	s_and_b64 vcc, exec, s[42:43]
	s_cbranch_vccz .LBB0_899

; __device__ __forceinline__ unsigned pk2(float lo, float hi) { f32x2_t v = {lo, hi}; bf16x2_t b = __builtin_convertvector(v, bf16x2_t); return __builtin_bit_cast(unsigned, b); }
; __device__ __forceinline__ float siluf_(float x) { return x * sigmoidf_(x); }
; #define RSTD_GET(ai, m) __int_as_float(__builtin_amdgcn_ds_bpermute(((m) * 16 + fr) << 2, __float_as_int((ai) ? es1 : es0)))
; __device__ __forceinline__ float row_rstd(const float* SS, int row) {
;     const f32x4* p = (const f32x4*)(SS + (size_t)row * 32);
;     float s = 0.f;
; #pragma unroll
;     for (int j = 0; j < 8; ++j) { const f32x4 a = p[j]; s += (a[0] + a[1]) + (a[2] + a[3]); }
;     return rsqrtf(s * (1.f / 1024.f) + EPS);
;     __device__ __forceinline__ void operator()(EPI_ARGS) const {
; #pragma unroll
;         for (int ai = 0; ai < 2; ++ai) {
;             if (ai == 1 && u.half) break;
; #pragma unroll
;             for (int m = 0; m < 4; ++m) {
;                 int row = EPI_ROWS(ai, m); asm volatile("" : "+v"(row)); const float rs = RSTD_GET(ai, m);
;                 float o[8];
; #pragma unroll
;                 for (int n = 0; n < 2; ++n)
; #pragma unroll
;                     for (int e = 0; e < 4; ++e) { const float g = acc[ai][0][m][n][e] * rs, up = acc[ai][1][m][n][e] * rs; o[n * 4 + e] = siluf_(g) * up; }
;                 u32x4 w; w.x = pk2(o[0], o[1]); w.y = pk2(o[2], o[3]); w.z = pk2(o[4], o[5]); w.w = pk2(o[6], o[7]);
;                 *(u32x4*)(T + (size_t)row * FF + u.pn * 128 + wc * 32 + 8 * fq) = w;
.LBB0_899:
	s_lshl_b32 s2, s63, 8
	v_mov_b32_e32 v247, 0
	v_add3_u32 v246, s2, v143, v142
	s_mov_b64 s[2:3], 0x4000
	v_lshlrev_b64 v[246:247], 7, v[246:247]
	v_lshl_add_u64 v[246:247], s[94:95], 0, v[246:247]
	v_lshl_add_u64 v[244:245], v[246:247], 0, s[2:3]
	global_load_dwordx4 v[204:207], v[246:247], off
	global_load_dwordx4 v[208:211], v[246:247], off offset:16
	global_load_dwordx4 v[212:215], v[246:247], off offset:32
	global_load_dwordx4 v[216:219], v[246:247], off offset:48
	global_load_dwordx4 v[220:223], v[246:247], off offset:64
	global_load_dwordx4 v[224:227], v[246:247], off offset:80
	global_load_dwordx4 v[228:231], v[246:247], off offset:96
	global_load_dwordx4 v[232:235], v[246:247], off offset:112
	global_load_dwordx4 v[236:239], v[244:245], off
	global_load_dwordx4 v[240:243], v[244:245], off offset:16
	global_load_dwordx4 v[180:183], v[244:245], off offset:32
	global_load_dwordx4 v[184:187], v[244:245], off offset:48
	global_load_dwordx4 v[190:193], v[244:245], off offset:64
	global_load_dwordx4 v[194:197], v[244:245], off offset:80
	global_load_dwordx4 v[160:163], v[244:245], off offset:96
	global_load_dwordx4 v[244:247], v[244:245], off offset:112
	s_lshl_b32 s26, s26, 8
	v_readlane_b32 s2, v255, 10
	v_readlane_b32 s3, v255, 11
	s_andn2_b64 vcc, exec, s[36:37]
	ds_bpermute_b32 v159, v145, v141
	v_add_u32_e32 v158, s26, v144
	s_nop 0
	v_mov_b64_e32 v[156:157], s[2:3]
	s_nop 0
	v_mad_i64_i32 v[154:155], s[38:39], v158, s71, v[156:157]
	s_lshl_b32 s2, s27, 7
	s_ashr_i32 s3, s2, 31
	s_lshl_b64 s[2:3], s[2:3], 1
	v_lshl_add_u64 v[154:155], v[154:155], 0, s[2:3]
	v_lshl_add_u64 v[154:155], v[154:155], 0, s[4:5]
	v_lshl_add_u64 v[154:155], v[154:155], 0, v[168:169]
	s_mov_b64 s[38:39], 0x16000
	s_waitcnt lgkmcnt(0)
	v_mul_f32_e32 v156, 0xbfb8aa3b, v159
	v_mul_f32_e32 v158, v159, v159
	ds_bpermute_b32 v159, v148, v141
	v_pk_mul_f32 v[120:121], v[120:121], v[124:125]
	v_pk_mul_f32 v[122:123], v[122:123], v[126:127]
	v_pk_mul_f32 v[112:113], v[112:113], v[116:117]
	v_pk_mul_f32 v[114:115], v[114:115], v[118:119]
	v_pk_mul_f32 v[124:125], v[124:125], v[156:157] op_sel_hi:[1,0]
	v_pk_mul_f32 v[126:127], v[126:127], v[156:157] op_sel_hi:[1,0]
	v_pk_mul_f32 v[116:117], v[116:117], v[156:157] op_sel_hi:[1,0]
	v_pk_mul_f32 v[118:119], v[118:119], v[156:157] op_sel_hi:[1,0]
	v_exp_f32_e32 v124, v124
	v_exp_f32_e32 v125, v125
	v_exp_f32_e32 v126, v126
	v_exp_f32_e32 v127, v127
	v_exp_f32_e32 v116, v116
	v_exp_f32_e32 v117, v117
	v_exp_f32_e32 v118, v118
	v_exp_f32_e32 v119, v119
	v_pk_add_f32 v[124:125], v[124:125], 1.0 op_sel_hi:[1,0]
	v_pk_add_f32 v[126:127], v[126:127], 1.0 op_sel_hi:[1,0]
	v_pk_add_f32 v[116:117], v[116:117], 1.0 op_sel_hi:[1,0]
	v_pk_add_f32 v[118:119], v[118:119], 1.0 op_sel_hi:[1,0]
	v_rcp_f32_e32 v124, v124
	v_rcp_f32_e32 v125, v125
	v_rcp_f32_e32 v126, v126
	v_rcp_f32_e32 v127, v127
	v_rcp_f32_e32 v116, v116
	v_rcp_f32_e32 v117, v117
	v_rcp_f32_e32 v118, v118
	v_rcp_f32_e32 v119, v119
	v_pk_mul_f32 v[120:121], v[120:121], v[158:159] op_sel_hi:[1,0]
	v_pk_mul_f32 v[122:123], v[122:123], v[158:159] op_sel_hi:[1,0]
	v_pk_mul_f32 v[112:113], v[112:113], v[158:159] op_sel_hi:[1,0]
	v_pk_mul_f32 v[114:115], v[114:115], v[158:159] op_sel_hi:[1,0]
	v_pk_mul_f32 v[120:121], v[120:121], v[124:125]
	v_pk_mul_f32 v[122:123], v[122:123], v[126:127]
	v_pk_mul_f32 v[112:113], v[112:113], v[116:117]
	v_pk_mul_f32 v[114:115], v[114:115], v[118:119]
	v_cvt_pk_bf16_f32 v124, v120, v121
	v_cvt_pk_bf16_f32 v125, v122, v123
	v_cvt_pk_bf16_f32 v126, v112, v113
	v_cvt_pk_bf16_f32 v127, v114, v115
	global_store_dwordx4 v[154:155], v[124:127], off
	v_lshl_add_u64 v[154:155], v[154:155], 0, s[38:39]
	s_waitcnt lgkmcnt(0)
	v_mul_f32_e32 v156, 0xbfb8aa3b, v159
	v_mul_f32_e32 v158, v159, v159
	ds_bpermute_b32 v159, v150, v141
	v_pk_mul_f32 v[104:105], v[104:105], v[108:109]
	v_pk_mul_f32 v[106:107], v[106:107], v[110:111]
	v_pk_mul_f32 v[96:97], v[96:97], v[100:101]
	v_pk_mul_f32 v[98:99], v[98:99], v[102:103]
	v_pk_mul_f32 v[108:109], v[108:109], v[156:157] op_sel_hi:[1,0]
	v_pk_mul_f32 v[110:111], v[110:111], v[156:157] op_sel_hi:[1,0]
	v_pk_mul_f32 v[100:101], v[100:101], v[156:157] op_sel_hi:[1,0]
	v_pk_mul_f32 v[102:103], v[102:103], v[156:157] op_sel_hi:[1,0]
	v_exp_f32_e32 v108, v108
	v_exp_f32_e32 v109, v109
	v_exp_f32_e32 v110, v110
	v_exp_f32_e32 v111, v111
	v_exp_f32_e32 v100, v100
	v_exp_f32_e32 v101, v101
	v_exp_f32_e32 v102, v102
	v_exp_f32_e32 v103, v103
	v_pk_add_f32 v[108:109], v[108:109], 1.0 op_sel_hi:[1,0]
	v_pk_add_f32 v[110:111], v[110:111], 1.0 op_sel_hi:[1,0]
	v_pk_add_f32 v[100:101], v[100:101], 1.0 op_sel_hi:[1,0]
	v_pk_add_f32 v[102:103], v[102:103], 1.0 op_sel_hi:[1,0]
	v_rcp_f32_e32 v108, v108
	v_rcp_f32_e32 v109, v109
	v_rcp_f32_e32 v110, v110
	v_rcp_f32_e32 v111, v111
	v_rcp_f32_e32 v100, v100
	v_rcp_f32_e32 v101, v101
	v_rcp_f32_e32 v102, v102
	v_rcp_f32_e32 v103, v103
	v_pk_mul_f32 v[104:105], v[104:105], v[158:159] op_sel_hi:[1,0]
	v_pk_mul_f32 v[106:107], v[106:107], v[158:159] op_sel_hi:[1,0]
	v_pk_mul_f32 v[96:97], v[96:97], v[158:159] op_sel_hi:[1,0]
	v_pk_mul_f32 v[98:99], v[98:99], v[158:159] op_sel_hi:[1,0]
	v_pk_mul_f32 v[104:105], v[104:105], v[108:109]
	v_pk_mul_f32 v[106:107], v[106:107], v[110:111]
	v_pk_mul_f32 v[96:97], v[96:97], v[100:101]
	v_pk_mul_f32 v[98:99], v[98:99], v[102:103]
	v_cvt_pk_bf16_f32 v108, v104, v105
	v_cvt_pk_bf16_f32 v109, v106, v107
	v_cvt_pk_bf16_f32 v110, v96, v97
	v_cvt_pk_bf16_f32 v111, v98, v99
	global_store_dwordx4 v[154:155], v[108:111], off
	v_lshl_add_u64 v[154:155], v[154:155], 0, s[38:39]
	s_waitcnt lgkmcnt(0)
; __device__ __forceinline__ unsigned pk2(float lo, float hi) { f32x2_t v = {lo, hi}; bf16x2_t b = __builtin_convertvector(v, bf16x2_t); return __builtin_bit_cast(unsigned, b); }
; __device__ __forceinline__ float siluf_(float x) { return x * sigmoidf_(x); }
; #define RSTD_GET(ai, m) __int_as_float(__builtin_amdgcn_ds_bpermute(((m) * 16 + fr) << 2, __float_as_int((ai) ? es1 : es0)))
;     __device__ __forceinline__ void operator()(EPI_ARGS) const {
;     ...
;             for (int m = 0; m < 4; ++m) {
;                 int row = EPI_ROWS(ai, m); asm volatile("" : "+v"(row)); const float rs = RSTD_GET(ai, m);
;                 float o[8];
; #pragma unroll
;                 for (int n = 0; n < 2; ++n)
; #pragma unroll
;                     for (int e = 0; e < 4; ++e) { const float g = acc[ai][0][m][n][e] * rs, up = acc[ai][1][m][n][e] * rs; o[n * 4 + e] = siluf_(g) * up; }
;                 u32x4 w; w.x = pk2(o[0], o[1]); w.y = pk2(o[2], o[3]); w.z = pk2(o[4], o[5]); w.w = pk2(o[6], o[7]);
;                 *(u32x4*)(T + (size_t)row * FF + u.pn * 128 + wc * 32 + 8 * fq) = w;
	v_mul_f32_e32 v156, 0xbfb8aa3b, v159
	v_mul_f32_e32 v158, v159, v159
	ds_bpermute_b32 v159, v152, v141
	v_pk_mul_f32 v[88:89], v[88:89], v[92:93]
	v_pk_mul_f32 v[90:91], v[90:91], v[94:95]
	v_pk_mul_f32 v[80:81], v[80:81], v[84:85]
	v_pk_mul_f32 v[82:83], v[82:83], v[86:87]
	v_pk_mul_f32 v[92:93], v[92:93], v[156:157] op_sel_hi:[1,0]
	v_pk_mul_f32 v[94:95], v[94:95], v[156:157] op_sel_hi:[1,0]
	v_pk_mul_f32 v[84:85], v[84:85], v[156:157] op_sel_hi:[1,0]
	v_pk_mul_f32 v[86:87], v[86:87], v[156:157] op_sel_hi:[1,0]
	v_exp_f32_e32 v92, v92
	v_exp_f32_e32 v93, v93
	v_exp_f32_e32 v94, v94
	v_exp_f32_e32 v95, v95
	v_exp_f32_e32 v84, v84
	v_exp_f32_e32 v85, v85
	v_exp_f32_e32 v86, v86
	v_exp_f32_e32 v87, v87
	v_pk_add_f32 v[92:93], v[92:93], 1.0 op_sel_hi:[1,0]
	v_pk_add_f32 v[94:95], v[94:95], 1.0 op_sel_hi:[1,0]
	v_pk_add_f32 v[84:85], v[84:85], 1.0 op_sel_hi:[1,0]
	v_pk_add_f32 v[86:87], v[86:87], 1.0 op_sel_hi:[1,0]
	v_rcp_f32_e32 v92, v92
	v_rcp_f32_e32 v93, v93
	v_rcp_f32_e32 v94, v94
	v_rcp_f32_e32 v95, v95
	v_rcp_f32_e32 v84, v84
	v_rcp_f32_e32 v85, v85
	v_rcp_f32_e32 v86, v86
	v_rcp_f32_e32 v87, v87
	v_pk_mul_f32 v[88:89], v[88:89], v[158:159] op_sel_hi:[1,0]
	v_pk_mul_f32 v[90:91], v[90:91], v[158:159] op_sel_hi:[1,0]
	v_pk_mul_f32 v[80:81], v[80:81], v[158:159] op_sel_hi:[1,0]
	v_pk_mul_f32 v[82:83], v[82:83], v[158:159] op_sel_hi:[1,0]
	v_pk_mul_f32 v[88:89], v[88:89], v[92:93]
	v_pk_mul_f32 v[90:91], v[90:91], v[94:95]
	v_pk_mul_f32 v[80:81], v[80:81], v[84:85]
	v_pk_mul_f32 v[82:83], v[82:83], v[86:87]
	v_cvt_pk_bf16_f32 v92, v88, v89
	v_cvt_pk_bf16_f32 v93, v90, v91
	v_cvt_pk_bf16_f32 v94, v80, v81
	v_cvt_pk_bf16_f32 v95, v82, v83
	global_store_dwordx4 v[154:155], v[92:95], off
	v_lshl_add_u64 v[154:155], v[154:155], 0, s[38:39]
	s_waitcnt lgkmcnt(0)
	v_mul_f32_e32 v156, 0xbfb8aa3b, v159
	v_mul_f32_e32 v158, v159, v159
	ds_bpermute_b32 v159, v145, v140
	v_pk_mul_f32 v[72:73], v[72:73], v[76:77]
	v_pk_mul_f32 v[74:75], v[74:75], v[78:79]
	v_pk_mul_f32 v[64:65], v[64:65], v[68:69]
	v_pk_mul_f32 v[66:67], v[66:67], v[70:71]
	v_pk_mul_f32 v[76:77], v[76:77], v[156:157] op_sel_hi:[1,0]
	v_pk_mul_f32 v[78:79], v[78:79], v[156:157] op_sel_hi:[1,0]
	v_pk_mul_f32 v[68:69], v[68:69], v[156:157] op_sel_hi:[1,0]
	v_pk_mul_f32 v[70:71], v[70:71], v[156:157] op_sel_hi:[1,0]
	v_exp_f32_e32 v76, v76
	v_exp_f32_e32 v77, v77
	v_exp_f32_e32 v78, v78
	v_exp_f32_e32 v79, v79
	v_exp_f32_e32 v68, v68
	v_exp_f32_e32 v69, v69
	v_exp_f32_e32 v70, v70
	v_exp_f32_e32 v71, v71
	v_pk_add_f32 v[76:77], v[76:77], 1.0 op_sel_hi:[1,0]
	v_pk_add_f32 v[78:79], v[78:79], 1.0 op_sel_hi:[1,0]
	v_pk_add_f32 v[68:69], v[68:69], 1.0 op_sel_hi:[1,0]
	v_pk_add_f32 v[70:71], v[70:71], 1.0 op_sel_hi:[1,0]
	v_rcp_f32_e32 v76, v76
	v_rcp_f32_e32 v77, v77
	v_rcp_f32_e32 v78, v78
	v_rcp_f32_e32 v79, v79
	v_rcp_f32_e32 v68, v68
	v_rcp_f32_e32 v69, v69
	v_rcp_f32_e32 v70, v70
	v_rcp_f32_e32 v71, v71
	v_pk_mul_f32 v[72:73], v[72:73], v[158:159] op_sel_hi:[1,0]
	v_pk_mul_f32 v[74:75], v[74:75], v[158:159] op_sel_hi:[1,0]
	v_pk_mul_f32 v[64:65], v[64:65], v[158:159] op_sel_hi:[1,0]
	v_pk_mul_f32 v[66:67], v[66:67], v[158:159] op_sel_hi:[1,0]
	v_pk_mul_f32 v[72:73], v[72:73], v[76:77]
	v_pk_mul_f32 v[74:75], v[74:75], v[78:79]
	v_pk_mul_f32 v[64:65], v[64:65], v[68:69]
	v_pk_mul_f32 v[66:67], v[66:67], v[70:71]
	v_cvt_pk_bf16_f32 v76, v72, v73
	v_cvt_pk_bf16_f32 v77, v74, v75
	v_cvt_pk_bf16_f32 v78, v64, v65
	v_cvt_pk_bf16_f32 v79, v66, v67
	s_mov_b64 s[38:39], 0x6e000
	global_store_dwordx4 v[154:155], v[76:79], off
	v_lshl_add_u64 v[154:155], v[154:155], 0, s[38:39]
	s_mov_b64 s[38:39], 0x16000
	s_waitcnt lgkmcnt(0)
	v_mul_f32_e32 v156, 0xbfb8aa3b, v159
	v_mul_f32_e32 v158, v159, v159
	ds_bpermute_b32 v159, v148, v140
	v_pk_mul_f32 v[56:57], v[56:57], v[60:61]
	v_pk_mul_f32 v[58:59], v[58:59], v[62:63]
	v_pk_mul_f32 v[48:49], v[48:49], v[52:53]
	v_pk_mul_f32 v[50:51], v[50:51], v[54:55]
	v_pk_mul_f32 v[60:61], v[60:61], v[156:157] op_sel_hi:[1,0]
	v_pk_mul_f32 v[62:63], v[62:63], v[156:157] op_sel_hi:[1,0]
	v_pk_mul_f32 v[52:53], v[52:53], v[156:157] op_sel_hi:[1,0]
	v_pk_mul_f32 v[54:55], v[54:55], v[156:157] op_sel_hi:[1,0]
	v_exp_f32_e32 v60, v60
	v_exp_f32_e32 v61, v61
	v_exp_f32_e32 v62, v62
	v_exp_f32_e32 v63, v63
	v_exp_f32_e32 v52, v52
	v_exp_f32_e32 v53, v53
	v_exp_f32_e32 v54, v54
	v_exp_f32_e32 v55, v55
	v_pk_add_f32 v[60:61], v[60:61], 1.0 op_sel_hi:[1,0]
	v_pk_add_f32 v[62:63], v[62:63], 1.0 op_sel_hi:[1,0]
	v_pk_add_f32 v[52:53], v[52:53], 1.0 op_sel_hi:[1,0]
	v_pk_add_f32 v[54:55], v[54:55], 1.0 op_sel_hi:[1,0]
	v_rcp_f32_e32 v60, v60
	v_rcp_f32_e32 v61, v61
	v_rcp_f32_e32 v62, v62
	v_rcp_f32_e32 v63, v63
	v_rcp_f32_e32 v52, v52
	v_rcp_f32_e32 v53, v53
	v_rcp_f32_e32 v54, v54
	v_rcp_f32_e32 v55, v55
	v_pk_mul_f32 v[56:57], v[56:57], v[158:159] op_sel_hi:[1,0]
	v_pk_mul_f32 v[58:59], v[58:59], v[158:159] op_sel_hi:[1,0]
	v_pk_mul_f32 v[48:49], v[48:49], v[158:159] op_sel_hi:[1,0]
	v_pk_mul_f32 v[50:51], v[50:51], v[158:159] op_sel_hi:[1,0]
	v_pk_mul_f32 v[56:57], v[56:57], v[60:61]
	v_pk_mul_f32 v[58:59], v[58:59], v[62:63]
	v_pk_mul_f32 v[48:49], v[48:49], v[52:53]
	v_pk_mul_f32 v[50:51], v[50:51], v[54:55]
	v_cvt_pk_bf16_f32 v60, v56, v57
	v_cvt_pk_bf16_f32 v61, v58, v59
	v_cvt_pk_bf16_f32 v62, v48, v49
	v_cvt_pk_bf16_f32 v63, v50, v51
	global_store_dwordx4 v[154:155], v[60:63], off
	v_lshl_add_u64 v[154:155], v[154:155], 0, s[38:39]
	s_waitcnt lgkmcnt(0)
; __device__ __forceinline__ unsigned pk2(float lo, float hi) { f32x2_t v = {lo, hi}; bf16x2_t b = __builtin_convertvector(v, bf16x2_t); return __builtin_bit_cast(unsigned, b); }
; __device__ __forceinline__ float siluf_(float x) { return x * sigmoidf_(x); }
; #define RSTD_GET(ai, m) __int_as_float(__builtin_amdgcn_ds_bpermute(((m) * 16 + fr) << 2, __float_as_int((ai) ? es1 : es0)))
; template <class Epi, class Sched>
; __device__ __forceinline__ void gemm_phase(const int tid, LAS unsigned char* lds, const int lda, const int ldb, const int K, const Sched& S, const Epi& E) {
;     ...
;         if (!has_next) break;
;     __device__ __forceinline__ void operator()(EPI_ARGS) const {
;     ...
;             for (int m = 0; m < 4; ++m) {
;                 int row = EPI_ROWS(ai, m); asm volatile("" : "+v"(row)); const float rs = RSTD_GET(ai, m);
;                 float o[8];
; #pragma unroll
;                 for (int n = 0; n < 2; ++n)
; #pragma unroll
;                     for (int e = 0; e < 4; ++e) { const float g = acc[ai][0][m][n][e] * rs, up = acc[ai][1][m][n][e] * rs; o[n * 4 + e] = siluf_(g) * up; }
;                 u32x4 w; w.x = pk2(o[0], o[1]); w.y = pk2(o[2], o[3]); w.z = pk2(o[4], o[5]); w.w = pk2(o[6], o[7]);
;                 *(u32x4*)(T + (size_t)row * FF + u.pn * 128 + wc * 32 + 8 * fq) = w;
	v_mul_f32_e32 v156, 0xbfb8aa3b, v159
	v_mul_f32_e32 v158, v159, v159
	ds_bpermute_b32 v159, v150, v140
	v_pk_mul_f32 v[40:41], v[40:41], v[44:45]
	v_pk_mul_f32 v[42:43], v[42:43], v[46:47]
	v_pk_mul_f32 v[32:33], v[32:33], v[36:37]
	v_pk_mul_f32 v[34:35], v[34:35], v[38:39]
	v_pk_mul_f32 v[44:45], v[44:45], v[156:157] op_sel_hi:[1,0]
	v_pk_mul_f32 v[46:47], v[46:47], v[156:157] op_sel_hi:[1,0]
	v_pk_mul_f32 v[36:37], v[36:37], v[156:157] op_sel_hi:[1,0]
	v_pk_mul_f32 v[38:39], v[38:39], v[156:157] op_sel_hi:[1,0]
	v_exp_f32_e32 v44, v44
	v_exp_f32_e32 v45, v45
	v_exp_f32_e32 v46, v46
	v_exp_f32_e32 v47, v47
	v_exp_f32_e32 v36, v36
	v_exp_f32_e32 v37, v37
	v_exp_f32_e32 v38, v38
	v_exp_f32_e32 v39, v39
	v_pk_add_f32 v[44:45], v[44:45], 1.0 op_sel_hi:[1,0]
	v_pk_add_f32 v[46:47], v[46:47], 1.0 op_sel_hi:[1,0]
	v_pk_add_f32 v[36:37], v[36:37], 1.0 op_sel_hi:[1,0]
	v_pk_add_f32 v[38:39], v[38:39], 1.0 op_sel_hi:[1,0]
	v_rcp_f32_e32 v44, v44
	v_rcp_f32_e32 v45, v45
	v_rcp_f32_e32 v46, v46
	v_rcp_f32_e32 v47, v47
	v_rcp_f32_e32 v36, v36
	v_rcp_f32_e32 v37, v37
	v_rcp_f32_e32 v38, v38
	v_rcp_f32_e32 v39, v39
	v_pk_mul_f32 v[40:41], v[40:41], v[158:159] op_sel_hi:[1,0]
	v_pk_mul_f32 v[42:43], v[42:43], v[158:159] op_sel_hi:[1,0]
	v_pk_mul_f32 v[32:33], v[32:33], v[158:159] op_sel_hi:[1,0]
	v_pk_mul_f32 v[34:35], v[34:35], v[158:159] op_sel_hi:[1,0]
	v_pk_mul_f32 v[40:41], v[40:41], v[44:45]
	v_pk_mul_f32 v[42:43], v[42:43], v[46:47]
	v_pk_mul_f32 v[32:33], v[32:33], v[36:37]
	v_pk_mul_f32 v[34:35], v[34:35], v[38:39]
	v_cvt_pk_bf16_f32 v44, v40, v41
	v_cvt_pk_bf16_f32 v45, v42, v43
	v_cvt_pk_bf16_f32 v46, v32, v33
	v_cvt_pk_bf16_f32 v47, v34, v35
	global_store_dwordx4 v[154:155], v[44:47], off
	v_lshl_add_u64 v[154:155], v[154:155], 0, s[38:39]
	s_waitcnt lgkmcnt(0)
	v_mul_f32_e32 v156, 0xbfb8aa3b, v159
	v_mul_f32_e32 v158, v159, v159
	ds_bpermute_b32 v159, v152, v140
	v_pk_mul_f32 v[24:25], v[24:25], v[28:29]
	v_pk_mul_f32 v[26:27], v[26:27], v[30:31]
	v_pk_mul_f32 v[16:17], v[16:17], v[20:21]
	v_pk_mul_f32 v[18:19], v[18:19], v[22:23]
	v_pk_mul_f32 v[28:29], v[28:29], v[156:157] op_sel_hi:[1,0]
	v_pk_mul_f32 v[30:31], v[30:31], v[156:157] op_sel_hi:[1,0]
	v_pk_mul_f32 v[20:21], v[20:21], v[156:157] op_sel_hi:[1,0]
	v_pk_mul_f32 v[22:23], v[22:23], v[156:157] op_sel_hi:[1,0]
	v_exp_f32_e32 v28, v28
	v_exp_f32_e32 v29, v29
	v_exp_f32_e32 v30, v30
	v_exp_f32_e32 v31, v31
	v_exp_f32_e32 v20, v20
	v_exp_f32_e32 v21, v21
	v_exp_f32_e32 v22, v22
	v_exp_f32_e32 v23, v23
	v_pk_add_f32 v[28:29], v[28:29], 1.0 op_sel_hi:[1,0]
	v_pk_add_f32 v[30:31], v[30:31], 1.0 op_sel_hi:[1,0]
	v_pk_add_f32 v[20:21], v[20:21], 1.0 op_sel_hi:[1,0]
	v_pk_add_f32 v[22:23], v[22:23], 1.0 op_sel_hi:[1,0]
	v_rcp_f32_e32 v28, v28
	v_rcp_f32_e32 v29, v29
	v_rcp_f32_e32 v30, v30
	v_rcp_f32_e32 v31, v31
	v_rcp_f32_e32 v20, v20
	v_rcp_f32_e32 v21, v21
	v_rcp_f32_e32 v22, v22
	v_rcp_f32_e32 v23, v23
	v_pk_mul_f32 v[24:25], v[24:25], v[158:159] op_sel_hi:[1,0]
	v_pk_mul_f32 v[26:27], v[26:27], v[158:159] op_sel_hi:[1,0]
	v_pk_mul_f32 v[16:17], v[16:17], v[158:159] op_sel_hi:[1,0]
	v_pk_mul_f32 v[18:19], v[18:19], v[158:159] op_sel_hi:[1,0]
	v_pk_mul_f32 v[24:25], v[24:25], v[28:29]
	v_pk_mul_f32 v[26:27], v[26:27], v[30:31]
	v_pk_mul_f32 v[16:17], v[16:17], v[20:21]
	v_pk_mul_f32 v[18:19], v[18:19], v[22:23]
	v_cvt_pk_bf16_f32 v28, v24, v25
	v_cvt_pk_bf16_f32 v29, v26, v27
	v_cvt_pk_bf16_f32 v30, v16, v17
	v_cvt_pk_bf16_f32 v31, v18, v19
	global_store_dwordx4 v[154:155], v[28:31], off
	v_lshl_add_u64 v[154:155], v[154:155], 0, s[38:39]
	s_waitcnt lgkmcnt(0)
	v_mul_f32_e32 v156, 0xbfb8aa3b, v159
	v_mul_f32_e32 v158, v159, v159
	v_pk_mul_f32 v[8:9], v[8:9], v[12:13]
	v_pk_mul_f32 v[10:11], v[10:11], v[14:15]
	v_pk_mul_f32 v[0:1], v[0:1], v[4:5]
	v_pk_mul_f32 v[2:3], v[2:3], v[6:7]
	v_pk_mul_f32 v[12:13], v[12:13], v[156:157] op_sel_hi:[1,0]
	v_pk_mul_f32 v[14:15], v[14:15], v[156:157] op_sel_hi:[1,0]
	v_pk_mul_f32 v[4:5], v[4:5], v[156:157] op_sel_hi:[1,0]
	v_pk_mul_f32 v[6:7], v[6:7], v[156:157] op_sel_hi:[1,0]
	v_exp_f32_e32 v12, v12
	v_exp_f32_e32 v13, v13
	v_exp_f32_e32 v14, v14
	v_exp_f32_e32 v15, v15
	v_exp_f32_e32 v4, v4
	v_exp_f32_e32 v5, v5
	v_exp_f32_e32 v6, v6
	v_exp_f32_e32 v7, v7
	v_pk_add_f32 v[12:13], v[12:13], 1.0 op_sel_hi:[1,0]
	v_pk_add_f32 v[14:15], v[14:15], 1.0 op_sel_hi:[1,0]
	v_pk_add_f32 v[4:5], v[4:5], 1.0 op_sel_hi:[1,0]
	v_pk_add_f32 v[6:7], v[6:7], 1.0 op_sel_hi:[1,0]
	v_rcp_f32_e32 v12, v12
	v_rcp_f32_e32 v13, v13
	v_rcp_f32_e32 v14, v14
	v_rcp_f32_e32 v15, v15
	v_rcp_f32_e32 v4, v4
	v_rcp_f32_e32 v5, v5
	v_rcp_f32_e32 v6, v6
	v_rcp_f32_e32 v7, v7
	v_pk_mul_f32 v[8:9], v[8:9], v[158:159] op_sel_hi:[1,0]
	v_pk_mul_f32 v[10:11], v[10:11], v[158:159] op_sel_hi:[1,0]
	v_pk_mul_f32 v[0:1], v[0:1], v[158:159] op_sel_hi:[1,0]
	v_pk_mul_f32 v[2:3], v[2:3], v[158:159] op_sel_hi:[1,0]
	v_pk_mul_f32 v[8:9], v[8:9], v[12:13]
	v_pk_mul_f32 v[10:11], v[10:11], v[14:15]
	v_pk_mul_f32 v[0:1], v[0:1], v[4:5]
	v_pk_mul_f32 v[2:3], v[2:3], v[6:7]
	v_cvt_pk_bf16_f32 v12, v8, v9
	v_cvt_pk_bf16_f32 v13, v10, v11
	v_cvt_pk_bf16_f32 v14, v0, v1
	v_cvt_pk_bf16_f32 v15, v2, v3
	s_mov_b64 s[2:3], -1
	global_store_dwordx4 v[154:155], v[12:15], off
	s_cbranch_vccnz .LBB0_891
; #define PG8_BAR __builtin_amdgcn_s_barrier()
; template <class Epi, class Sched>
; __device__ __forceinline__ void gemm_phase(const int tid, LAS unsigned char* lds, const int lda, const int ldb, const int K, const Sched& S, const Epi& E) {
;     ...
;         E.pre(nxt, wr, wc, fr, fq, es0, es1);
;         E.init(acc, nxt, wr, wc, fr, fq);
;         cur = nxt; cA = nA; cB = nB; ++ui;
;         if (wr == 1) PG8_BAR;
; __device__ __forceinline__ float row_rstd(const float* SS, int row) {
;     const f32x4* p = (const f32x4*)(SS + (size_t)row * 32);
;     float s = 0.f;
; #pragma unroll
;     for (int j = 0; j < 8; ++j) { const f32x4 a = p[j]; s += (a[0] + a[1]) + (a[2] + a[3]); }
;     return rsqrtf(s * (1.f / 1024.f) + EPS);
	s_waitcnt vmcnt(8)
	v_add_f32_e32 v4, v204, v205
	v_add_f32_e32 v6, v236, v237
	v_add_f32_e32 v5, v206, v207
	v_add_f32_e32 v7, v238, v239
	v_add_f32_e32 v1, v4, v5
	v_add_f32_e32 v0, v6, v7
	v_add_f32_e32 v1, 0, v1
	v_add_f32_e32 v0, 0, v0
	v_add_f32_e32 v4, v208, v209
	v_add_f32_e32 v6, v240, v241
	v_add_f32_e32 v5, v210, v211
	v_add_f32_e32 v7, v242, v243
	v_add_f32_e32 v4, v4, v5
	v_add_f32_e32 v6, v6, v7
	v_add_f32_e32 v1, v1, v4
	v_add_f32_e32 v0, v0, v6
	v_add_f32_e32 v4, v212, v213
	v_add_f32_e32 v6, v180, v181
	v_add_f32_e32 v5, v214, v215
	v_add_f32_e32 v7, v182, v183
	v_add_f32_e32 v4, v4, v5
	v_add_f32_e32 v6, v6, v7
	v_add_f32_e32 v1, v1, v4
	v_add_f32_e32 v0, v0, v6
	v_add_f32_e32 v4, v216, v217
	v_add_f32_e32 v6, v184, v185
	v_add_f32_e32 v5, v218, v219
	v_add_f32_e32 v7, v186, v187
	v_add_f32_e32 v4, v4, v5
	v_add_f32_e32 v6, v6, v7
	v_add_f32_e32 v1, v1, v4
	v_add_f32_e32 v0, v0, v6
	v_add_f32_e32 v4, v220, v221
	v_add_f32_e32 v6, v190, v191
	v_add_f32_e32 v5, v222, v223
	v_add_f32_e32 v7, v192, v193
	v_add_f32_e32 v4, v4, v5
	v_add_f32_e32 v6, v6, v7
	v_add_f32_e32 v1, v1, v4
	v_add_f32_e32 v0, v0, v6
	v_add_f32_e32 v4, v224, v225
	v_add_f32_e32 v6, v194, v195
	v_add_f32_e32 v5, v226, v227
	v_add_f32_e32 v7, v196, v197
	v_add_f32_e32 v4, v4, v5
	v_add_f32_e32 v6, v6, v7
	v_add_f32_e32 v1, v1, v4
	v_add_f32_e32 v0, v0, v6
	v_add_f32_e32 v4, v228, v229
	v_add_f32_e32 v6, v160, v161
	v_add_f32_e32 v5, v230, v231
	v_add_f32_e32 v7, v162, v163
	v_add_f32_e32 v4, v4, v5
	v_add_f32_e32 v6, v6, v7
	v_add_f32_e32 v1, v1, v4
	v_add_f32_e32 v0, v0, v6
	v_add_f32_e32 v4, v232, v233
	v_add_f32_e32 v6, v244, v245
	v_add_f32_e32 v5, v234, v235
	v_add_f32_e32 v7, v246, v247
	v_add_f32_e32 v4, v4, v5
	v_add_f32_e32 v6, v6, v7
	v_add_f32_e32 v1, v1, v4
	v_add_f32_e32 v0, v0, v6
	s_mov_b32 s2, 0x3a800000
	s_andn2_b64 vcc, exec, s[22:23]
	s_nop 0
	v_pk_fma_f32 v[0:1], v[0:1], s[2:3], v[170:171] op_sel_hi:[1,0,0]
	s_nop 0
	v_cmp_gt_f32_e64 s[36:37], s33, v0
	v_cmp_gt_f32_e64 s[38:39], s33, v1
	s_cbranch_vccnz .LBB0_890
	s_nop 0
	s_branch .LBB0_890
